# stack18 + prologue wave index relabelled (61st item spread over all workgroups) + scan2 item preamble: step-0 M/N loads issued behind the initial-state loads, split afterwards (one global round trip p
# baseline (speedup 1.0000x reference)
; __device__ __forceinline__ int lane_id_asm() { int v; asm volatile("v_mbcnt_lo_u32_b32 %0, -1, 0\n\tv_mbcnt_hi_u32_b32 %0, -1, %0" : "=v"(v)); return v; }
; #define GAS __attribute__((address_space(1)))
; #define LAS __attribute__((address_space(3)))
; #define LDS_WAIT() asm volatile("s_waitcnt lgkmcnt(0)" ::: "memory")
; __device__ __forceinline__ kptr_t kargs() { kptr_t p = (kptr_t)__builtin_amdgcn_kernarg_segment_ptr(); asm volatile("" : "+s"(p)); return p; }
; template <class T> __device__ __forceinline__ T* launder_s(T* p) { asm volatile("" : "+s"(p)); return p; }
; __device__ __forceinline__ int launder_si(int v) { asm volatile("" : "+s"(v)); return v; }
; __device__ __forceinline__ void p0_transpose_item(const float* W, int K, int N, bf16* WT, LAS float* scr, int item, int lane) {
;     const int nblk = N / 32, kb = item / nblk, nb = item % nblk, k0 = 64 * kb, n0 = 32 * nb;
; #pragma unroll 8
;     for (int i = 0; i < 32; ++i) { const int kk = 2 * i + (lane >> 5); scr[kk * 33 + (lane & 31)] = ((const GAS float*)W)[(size_t)(k0 + kk) * N + n0 + (lane & 31)]; }
;     LDS_WAIT(); asm volatile("" ::: "memory");
;     const int c = lane & 7;
; #pragma unroll
;     for (int j = 0; j < 4; ++j) { const int n = (lane >> 3) + 8 * j; const LAS float* s = scr + (8 * c) * 33 + n;
; __device__ __forceinline__ void phase_prologue(Frame& F) {
;     const kptr_t ka = kargs(); const int lane = lane_id_asm(), tid = F.wave * 64 + lane; (void)tid; (void)ka;
;     unsigned char* const ws_ = launder_s(F.ws); float* const out_ = launder_s(F.out); (void)ws_; (void)out_;
;     LAS float* scr = (LAS float*)(F.lds + RING_OFF + F.wave * 16384);
;     const int gw = launder_si(F.vcu * NWAVES + F.wave), NGW = F.G * NWAVES;
;     constexpr int I_IN = (D / 64) * (DIN / 32), I_OC = (DC / 64) * (D / 32), I_O = (D / 64) * (D / 32), I_UP = (D / 64) * (DFF / 32), I_DN = (DFF / 64) * (D / 32);
;     constexpr int PER_L = I_IN + 2 * I_OC + I_O + I_UP + I_DN, NITEMS = NL * PER_L;
;     for (int it = gw; it < NITEMS; it += NGW) {
.LBB0_20:
	s_nop 0
	v_readlane_b32 s0, v254, 0
	v_readlane_b32 s1, v254, 1
	s_load_dwordx4 s[4:7], s[0:1], 0xd0
	s_mov_b64 s[10:11], s[0:1]
	s_lshl_b32 s1, s37, 3
	v_mbcnt_lo_u32_b32 v37, -1, 0
	v_mbcnt_hi_u32_b32 v37, -1, v37
	s_waitcnt lgkmcnt(0)
	s_mov_b64 s[14:15], s[6:7]
	s_mov_b64 s[12:13], s[4:5]
	s_mov_b64 s[4:5], s[14:15]
	s_mov_b64 s[6:7], s[12:13]
	s_add_i32 s8, s1, s47
	s_mov_b32 s6, s8
	v_writelane_b32 v254, s6, 12
	s_mov_b32 s1, s8
	s_and_b32 s98, s1, 7
	s_lshl_b32 s98, s98, 8
	s_lshr_b32 s1, s1, 3
	s_add_i32 s1, s1, s98
	s_lshl_b32 s44, s33, 3
	v_writelane_b32 v254, s7, 13
	s_cmp_gt_i32 s1, 0x1e3ff
	s_cbranch_scc1 .LBB0_55
	s_lshl_b32 s3, s47, 14
	s_add_i32 s6, s3, 0
	s_add_u32 s3, s4, 0x16500000
	s_addc_u32 s16, s5, 0
	s_add_u32 s18, s4, 0xe500000
	s_addc_u32 s19, s5, 0
	s_add_u32 s20, s4, 0xc500000
	s_addc_u32 s21, s5, 0
	s_add_u32 s22, s4, 0xb500000
	s_addc_u32 s23, s5, 0
	v_lshlrev_b32_e32 v1, 3, v37
	s_add_u32 s24, s4, 0xa500000
	v_ashrrev_i32_e32 v0, 5, v37
	v_ashrrev_i32_e32 v39, 3, v37
	v_and_b32_e32 v6, 56, v1
	s_addc_u32 s25, s5, 0
	v_and_b32_e32 v2, 31, v37
	v_mul_u32_u24_e32 v1, 0x84, v6
	v_lshlrev_b32_e32 v5, 2, v39
	s_add_u32 s26, s4, 0x100000
	v_add_u32_e32 v8, 4, v0
	v_add_u32_e32 v10, 8, v0
	v_add_u32_e32 v12, 12, v0
	v_add_u32_e32 v14, 16, v0
	v_add_u32_e32 v16, 20, v0
	v_add_u32_e32 v18, 24, v0
	v_add_u32_e32 v20, 28, v0
	v_mov_b32_e32 v3, 0
	v_lshl_add_u32 v4, v2, 2, s6
	s_movk_i32 s17, 0x84
	v_add3_u32 v40, s6, v1, v5
	v_add_u32_e32 v41, 8, v39
	v_add_u32_e32 v42, 16, v39
	v_add_u32_e32 v43, 24, v39
	s_addc_u32 s27, s5, 0
	v_mov_b32_e32 v1, v0
	v_mov_b32_e32 v5, v8
	v_mov_b32_e32 v7, v10
	v_mov_b32_e32 v9, v12
	v_mov_b32_e32 v11, v14
	v_mov_b32_e32 v13, v16
	v_mov_b32_e32 v15, v18
	v_mov_b32_e32 v17, v20
	s_mov_b32 s28, 0xa400
	v_lshlrev_b32_e32 v2, 2, v2
	s_branch .LBB0_23

; #define GAS __attribute__((address_space(1)))
; #define INP(k) (*(const float* const __attribute__((address_space(4)))*)(ka + 8 * (k)))
; __device__ __forceinline__ void phase_scan2(Frame& F, int l) {
;     ...
;         const bool samp = item >= NPI; const int q = samp ? item - NPI : item, seq = q >> 2, rq = q & 3, b = seq >> 4, h = seq & 15;
;         const int nch = samp ? 1 : TP / 64, cidx0 = samp ? BP * NH * 64 + seq : seq * 64, m0 = samp ? MP + b * TS : b * TP;
;         f32x4 sD = {0.f, 0.f, 0.f, 0.f};
;         if (samp && w < 4) { const GAS float* sp = (const GAS float*)(INP(4) + ((((size_t)l * BS + b) * NH + h) * HD + rq * 16 + 4 * fq) * HD + 16 * w + fr);
; #pragma unroll
;             for (int r = 0; r < 4; ++r) sD[r] = sp[r * 64]; }
.LBB0_634:
	s_waitcnt vmcnt(4)
	s_cmpk_lt_i32 s0, 0x100
	s_cselect_b64 s[30:31], -1, 0
	s_add_i32 s1, s0, 0xffffff00
	s_cmpk_gt_i32 s0, 0xff
	s_cselect_b64 s[24:25], -1, 0
	s_and_b64 s[8:9], s[24:25], exec
	s_cselect_b32 s10, s1, s0
	s_ashr_i32 s35, s10, 2
	s_and_b64 s[8:9], s[24:25], s[4:5]
	s_and_b32 s34, s10, 3
	s_ashr_i32 s26, s10, 6
	s_andn2_b64 vcc, exec, s[8:9]
	s_and_b32 s1, s35, 15
	s_cbranch_vccnz .LBB0_636
	s_load_dwordx2 s[8:9], s[12:13], 0x20
	s_ashr_i32 s27, s26, 31
	s_lshl_b64 s[28:29], s[26:27], 4
	s_add_u32 s11, s28, s18
	s_addc_u32 s29, s29, s19
	s_or_b32 s28, s11, s1
	s_lshl_b32 s92, s34, 4
	s_lshl_b64 s[28:29], s[28:29], 14
	v_lshl_add_u64 v[2:3], s[92:93], 0, v[44:45]
	s_waitcnt lgkmcnt(0)
	s_add_u32 s8, s8, s28
	v_lshlrev_b64 v[2:3], 8, v[2:3]
	s_addc_u32 s9, s9, s29
	v_lshl_add_u64 v[2:3], s[8:9], 0, v[2:3]
	s_mov_b32 s21, s93
	v_lshl_add_u64 v[2:3], v[2:3], 0, s[20:21]
	v_mov_b32_e32 v55, v1
	v_lshl_add_u64 v[2:3], v[2:3], 0, v[54:55]
	global_load_dword v36, v[2:3], off
	global_load_dword v37, v[2:3], off offset:256
	global_load_dword v38, v[2:3], off offset:512
	global_load_dword v39, v[2:3], off offset:768
	v_cndmask_b32_e64 v0, 0, 1, s[4:5]
	v_cmp_ne_u32_e64 s[8:9], 1, v0
	s_branch .LBB0_638

; #define S2_SPLIT() do { if (w < 4) { _Pragma("unroll") for (int r = 0; r < 4; ++r) { const unsigned hb = f2bf(sD[r]); const float lo = sD[r] - bf_lo(hb); \
;             SH[(4 * fq + r) * CP + 16 * w + fr] = (bf16)hb; SL[(4 * fq + r) * CP + 16 * w + fr] = (bf16)f2bf(lo); } } } while (0)
; #define S2_LOAD(st, M_, N_) do { if ((st) < nch) { const size_t mb_ = (size_t)(m0 + (st) * 64); \
;             M_ = *(const GAS v4u*)(WDb + (mb_ + mrow) * 2048 + h * 128 + mc8); \
;             if (tid < 128) N_ = *(const GAS v4u*)(AAb + (mb_ + rq * 16 + mrow) * DC + h * 64 + mc8); } } while (0)
; __device__ __forceinline__ void phase_scan2(Frame& F, int l) {
;     ...
;         S2_SPLIT();
;         v4u am, an, bm, bn, cm, cn, dm, dn;
;     ...
;         S2_LOAD(0, am, an); S2_LOAD(1, bm, bn); S2_LOAD(2, cm, cn); S2_LOAD(3, dm, dn);
.LBB0_638:
	s_andn2_b32 s10, s10, 63
	s_add_i32 s27, s10, 0x4000
	s_lshl_b32 s21, s26, 12
	s_and_b64 s[10:11], s[24:25], exec
	s_cselect_b32 s28, s27, s21
	s_ashr_i32 s29, s28, 31
	v_lshl_add_u64 v[2:3], s[28:29], 0, v[42:43]
	v_lshlrev_b64 v[32:33], 12, v[2:3]
	v_lshl_add_u64 v[32:33], s[14:15], 0, v[32:33]
	s_lshl_b32 s10, s1, 8
	s_mov_b32 s11, s93
	v_lshl_add_u64 v[32:33], v[32:33], 0, s[10:11]
	v_lshlrev_b32_e32 v0, 1, v40
	v_lshl_add_u64 v[32:33], v[32:33], 0, v[0:1]
	global_load_dwordx4 v[32:35], v[32:33], off
	s_lshl_b32 s92, s1, 7
	s_and_saveexec_b64 s[10:11], s[6:7]
	s_cbranch_execz .LBB0_640
	s_lshl_b32 s36, s34, 4
	s_mov_b32 s37, s93
	v_lshl_add_u64 v[2:3], v[2:3], 0, s[36:37]
	v_lshlrev_b64 v[2:3], 11, v[2:3]
	v_lshl_add_u64 v[2:3], s[16:17], 0, v[2:3]
	v_lshl_add_u64 v[2:3], v[2:3], 0, s[92:93]
	v_lshl_add_u64 v[2:3], v[2:3], 0, v[0:1]
	global_load_dwordx4 v[20:23], v[2:3], off
.LBB0_640:
	s_or_b64 exec, exec, s[10:11]
	s_andn2_b64 vcc, exec, s[4:5]
	s_cbranch_vccnz .Ls2_rest
.LBB0_637:
	s_waitcnt vmcnt(4)
	v_cvt_pk_bf16_f32 v0, v36, v36
	v_lshlrev_b32_e32 v2, 16, v0
	v_sub_f32_e32 v2, v36, v2
	ds_write_b16 v70, v0 offset:26624
	v_cvt_pk_bf16_f32 v0, v2, s0
	ds_write_b16 v70, v0 offset:28928
	s_waitcnt vmcnt(3)
	v_cvt_pk_bf16_f32 v0, v37, v37
	v_lshlrev_b32_e32 v2, 16, v0
	v_sub_f32_e32 v2, v37, v2
	ds_write_b16 v70, v0 offset:26768
	v_cvt_pk_bf16_f32 v0, v2, s0
	ds_write_b16 v70, v0 offset:29072
	s_waitcnt vmcnt(2)
	v_cvt_pk_bf16_f32 v0, v38, v38
	v_lshlrev_b32_e32 v2, 16, v0
	v_sub_f32_e32 v2, v38, v2
	ds_write_b16 v70, v0 offset:26912
	v_cvt_pk_bf16_f32 v0, v2, s0
	ds_write_b16 v70, v0 offset:29216
	s_waitcnt vmcnt(1)
	v_cvt_pk_bf16_f32 v0, v39, v39
	v_lshlrev_b32_e32 v2, 16, v0
	v_sub_f32_e32 v2, v39, v2
	ds_write_b16 v71, v0 offset:26624
	v_cvt_pk_bf16_f32 v0, v2, s0
	ds_write_b16 v71, v0 offset:28928
.Ls2_rest:
	v_lshlrev_b32_e32 v0, 1, v40
	v_cndmask_b32_e64 v2, 0, 1, s[30:31]
	v_cmp_ne_u32_e64 s[10:11], 1, v2
	s_andn2_b64 vcc, exec, s[30:31]
	s_cbranch_vccz .LBB0_645
	s_and_b64 vcc, exec, s[10:11]
	s_cbranch_vccz .LBB0_648
